# v24 + one static s_setprio 1 for waves 4-7 (younger half) for the duration of the two attention phases, reset to 0 before the following GEMM phases
# baseline (speedup 1.0000x reference)
; #define LAS __attribute__((address_space(3)))
; template <int MODE> __device__ __forceinline__ void attn_unit(const AU& U, LAS unsigned char* lds, const float* rope, const float* biasg) {
;     ...
;     const int glo = MODE == 1 ? (g0 > 8 ? g0 - 8 : 0) : 0, ghi = (U.qpos0 + U.nrows - 1) >> 6;
;     const int qpos = U.qpos0 + 32 * w + r;
;     LAS float* biasl = (LAS float*)(lds + BIAS_OFF);
;     if (MODE == 1) { for (int i = tid; i < 320; i += 512) biasl[i] = biasg[U.h * 320 + 319 - i] * LOG2E; }
; __global__ void __launch_bounds__(512, 2) fwd(Args args) {
;     ...
;     for (int rep_ = 0; rep_ < PROBE_P4; ++rep_) if (IN(4)) {
;         constexpr int NU = 2560;
;         for (int rd = 0; rd * G < NU; ++rd) { const int i = rd * G + ((rd & 1) ? (G - 1 - bx) : bx); if (i >= NU) continue;
.LBB0_451:
	s_cmp_lt_i32 s78, 5
	s_cselect_b64 s[28:29], -1, 0
	s_and_b64 s[0:1], s[28:29], s[0:1]
	s_andn2_b64 vcc, exec, s[0:1]
	s_cbranch_vccnz .LBB0_755
	v_readfirstlane_b32 s98, v198
	s_nop 3
	s_lshr_b32 s98, s98, 8
	s_cmp_eq_u32 s98, 0
	s_cbranch_scc1 .Lprio4_done
	s_setprio 1
.Lprio4_done:
	s_not_b32 s0, s74
	s_add_i32 s24, s96, s0
	v_readlane_b32 s0, v251, 59
	v_readlane_b32 s8, v250, 3
	v_readlane_b32 s9, v250, 4
	s_cmp_eq_u64 s[8:9], 0
	s_cselect_b64 s[30:31], -1, 0
	s_cmp_lg_u64 s[8:9], 0
	s_mov_b32 s0, 0xc800
	s_cselect_b64 s[34:35], -1, 0
	s_add_i32 s48, s0, 0x100
	s_movk_i32 s40, 0xff00
	s_mov_b32 s0, 0xc400
	s_mov_b32 s37, 0
	s_movk_i32 s25, 0x140
	s_movk_i32 s39, 0x2a00
	s_movk_i32 s43, 0x29ff
	s_movk_i32 s46, 0x200
	s_movk_i32 s47, 0x100
	s_mov_b32 s38, 0x3fb8aa3b
	s_movk_i32 s49, 0x400
	s_movk_i32 s50, 0xff3f
	s_movk_i32 s51, 0x1600
	v_mov_b32_e32 v3, 0
	s_movk_i32 s52, 0xc0
	s_movk_i32 s53, 0x90
	s_mov_b32 s41, -1
	s_movk_i32 s54, 0x900
	s_add_i32 s55, s0, 0x100
	s_mov_b32 s42, 0x3e38aa3b
	s_movk_i32 s56, 0xffc1
	s_movk_i32 s57, 0xffe1
	s_mov_b32 s58, 0x40c00000
	s_movk_i32 s59, 0x600
	s_movk_i32 s60, 0x7fff
	s_mov_b32 s61, 0x7060302
	s_movk_i32 s62, 0x500
	s_mov_b32 s63, 0x66666667
	s_movk_i32 s64, 0xffc0
	s_movk_i32 s65, 0xd0
	s_movk_i32 s66, 0x300
	s_movk_i32 s67, 0xb00
	s_mov_b32 s68, 0x58000
	v_mov_b32_e32 v1, 0x100
	v_mov_b32_e32 v201, 0x120
	v_mov_b32_e32 v203, 0x200
	v_mov_b32_e32 v236, 0x400
	v_mov_b32_e32 v237, 0x58000
	s_mov_b32 s0, 0
	s_mov_b32 s69, 0
	v_readlane_b32 s1, v251, 60
	v_readlane_b32 s2, v251, 61
	v_readlane_b32 s3, v251, 62
	v_readlane_b32 s4, v251, 63
	v_readlane_b32 s5, v250, 0
	v_readlane_b32 s6, v250, 1
	v_readlane_b32 s7, v250, 2
	v_readlane_b32 s10, v250, 5
	v_readlane_b32 s11, v250, 6
	v_readlane_b32 s12, v250, 7
	v_readlane_b32 s13, v250, 8
	v_readlane_b32 s14, v250, 9
	v_readlane_b32 s15, v250, 10
	s_branch .LBB0_456

; __device__ __forceinline__ unsigned xb_ld(unsigned* p)              { return __hip_atomic_load(p, __ATOMIC_RELAXED, __HIP_MEMORY_SCOPE_AGENT); }
; __device__ __forceinline__ void xcd_barrier_complete(unsigned* bar, unsigned x, unsigned& nloc, unsigned& nx) {
;     const unsigned G = gridDim.x * gridDim.y * gridDim.z;
;     unsigned sum, cnt, mine, sp = 0u;
;     for (;;) {
;         sum = 0u; cnt = 0u; mine = 0u;
; #pragma unroll
;         for (unsigned j = 0; j < 16; ++j) { const unsigned c = xb_ld(&bar[XB_XCNT(j)]); sum += c; cnt += (c > 0u) ? 1u : 0u; mine = (j == x) ? c : mine; }
;         if (sum == G) break;
;         __builtin_amdgcn_s_sleep(1);
;         if ((++sp & 255u) == 0u) { if (xb_ld(&bar[XB_TMO])) break; if (sp > XB_SPIN_CAP) { atomicAdd(&bar[XB_TMO], 1u); break; } }
;     }
;     nloc = mine > 0u ? mine : 1u; nx = cnt > 0u ? cnt : 1u;
; }
; __device__ __forceinline__ void xcd_barrier(const XcdBarrier& b) {
;     asm volatile("s_waitcnt vmcnt(0)" ::: "memory");
;     __syncthreads();
;     if (threadIdx.x == 0) {
;         unsigned* bar = b.bar;
;         __builtin_amdgcn_s_waitcnt(0);
;         unsigned nloc = b.st[0], nx = b.st[1];
;         if (nloc == 0u) { xcd_barrier_complete(bar, b.x, nloc, nx); b.st[0] = nloc; b.st[1] = nx; }
.LBB0_755:
	s_setprio 0
	s_cmp_gt_i32 s79, 5
	s_cselect_b64 s[0:1], -1, 0
	s_and_b64 s[2:3], s[28:29], s[0:1]
	v_readlane_b32 s60, v251, 51
	v_readlane_b32 s56, v251, 49
	s_and_b64 vcc, exec, s[2:3]
	v_readlane_b32 s61, v251, 52
	v_readlane_b32 s59, v251, 57
	v_readlane_b32 s64, v251, 58
	v_readlane_b32 s65, v251, 55
	v_readlane_b32 s66, v251, 56
	v_readlane_b32 s57, v251, 50
	s_cbranch_vccz .LBB0_809
	s_waitcnt vmcnt(0)
	s_waitcnt vmcnt(0)
	s_barrier
	s_mov_b64 s[4:5], exec
	v_readlane_b32 s2, v251, 9
	v_readlane_b32 s3, v251, 10
	s_and_b64 s[2:3], s[4:5], s[2:3]
	s_mov_b64 exec, s[2:3]
	s_cbranch_execz .LBB0_808
	s_add_u32 s6, s76, 0x4200
	s_mov_b32 s2, 0x20160
	s_addc_u32 s7, s77, 0
	s_addk_i32 s2, 0x100
	v_mov_b32_e32 v1, s2
	s_mov_b32 s2, 0x20164
	s_waitcnt vmcnt(0) expcnt(0) lgkmcnt(0)
	ds_read_b32 v3, v1
	s_addk_i32 s2, 0x100
	v_mov_b32_e32 v1, s2
	ds_read_b32 v1, v1
	s_waitcnt lgkmcnt(1)
	v_cmp_ne_u32_e32 vcc, 0, v3
	s_cbranch_vccnz .LBB0_772
	v_readlane_b32 s8, v251, 1
	v_readlane_b32 s2, v251, 0
	v_readlane_b32 s9, v251, 2
	s_add_u32 s8, s76, 0x4400
	s_mul_i32 s2, s2, s9
	s_addc_u32 s9, s77, 0
	s_add_u32 s10, s76, 0x4500
	s_addc_u32 s11, s77, 0
	s_add_u32 s12, s76, 0x4600
	s_addc_u32 s13, s77, 0
	s_add_u32 s14, s76, 0x4700
	s_addc_u32 s15, s77, 0
	s_add_u32 s16, s76, 0x4800
	s_addc_u32 s17, s77, 0
	s_add_u32 s18, s76, 0x4900
	s_addc_u32 s19, s77, 0
	s_add_u32 s20, s76, 0x4a00
	s_addc_u32 s21, s77, 0
	s_add_u32 s22, s76, 0x4b00
	s_addc_u32 s23, s77, 0
	s_add_u32 s24, s76, 0x4c00
	s_addc_u32 s25, s77, 0
	s_add_u32 s26, s76, 0x4d00
	s_addc_u32 s27, s77, 0
	s_add_u32 s28, s76, 0x4e00
	s_addc_u32 s29, s77, 0
	s_add_u32 s30, s76, 0x4f00
	s_addc_u32 s31, s77, 0
	s_add_u32 s34, s76, 0x5000
	s_addc_u32 s35, s77, 0
	s_add_u32 s36, s76, 0x5100
	s_addc_u32 s37, s77, 0
	s_add_u32 s38, s76, 0x5200
	s_addc_u32 s39, s77, 0
	s_add_u32 s40, s76, 0x5300
	s_mul_i32 s2, s2, s96
	s_addc_u32 s41, s77, 0
	s_mov_b32 s3, 1
	v_mov_b32_e32 v17, 0
	s_branch .LBB0_760

; #define LAS __attribute__((address_space(3)))
; template <bool SMP> __device__ __forceinline__ void sb_unit4(const bf16* Hb, const float* c_sk, const float* c_sv, bf16* O, int b, int c, int hg, LAS unsigned char* lds) {
;     using namespace att;
;     int tid = threadIdx.x; asm volatile("" : "+v"(tid));
;     const int lane = tid & 63, r = lane & 31, hi = lane >> 5, w = __builtin_amdgcn_readfirstlane(tid >> 6), hw = w >> 1, half = w & 1;
;     const int tq = SMP ? 16 : c;
;     const size_t qrow = (SMP ? (size_t)MP + b * 64 : (size_t)b * SEQ + (size_t)c * 64) + 32 * half + r;
;     const int qpos = tq * 64 + 32 * half + r;
;     bf16x8 qf[4];
; #pragma unroll
;     for (int s = 0; s < 4; ++s) qf[s] = *(const bf16x8*)(Hb + qrow * IN_C + (hg * 4 + hw) * 64 + 16 * s + 8 * hi);
;     f32x16 o0, o1;
; #pragma unroll
;     for (int i = 0; i < 16; ++i) { o0[i] = 0.f; o1[i] = 0.f; }
;     float carry = 1.f;
;     v4u pre[8];
;     sb_loads<SMP>(Hb, c_sk, c_sv, b, c, hg, tq, tid, pre);
;     LAS unsigned char* hb = lds + hw * SB_HB;
;     const int vlane = (4 * hi + ((lane & 15) >> 2)) * 144 + ((lane >> 4) & 1) * 32 + (lane & 3) * 8;
; __global__ void __launch_bounds__(512, 2) fwd(Args args) {
;     ...
;     for (int rep_ = 0; rep_ < PROBE_P11; ++rep_) if (IN(11)) {
;         constexpr int NU = 2048 + 128;
;         for (int i = bx; i < NU; i += G) {
;             if (i < 2048) sb_unit4<false>(Hb, c_sk, c_sv, O1b, i >> 8, (i >> 2) & 63, i & 3, lds);
;             else { const int j = i - 2048; sb_unit4<true>(Hb, c_sk, c_sv, O1b, j >> 2, 0, j & 3, lds); }
.LBB0_1342:
	s_cmp_lt_i32 s78, 12
	s_cselect_b64 s[2:3], -1, 0
	v_writelane_b32 v250, s2, 11
	s_and_b64 s[0:1], s[2:3], s[0:1]
	s_cmpk_lt_i32 s74, 0x880
	v_writelane_b32 v250, s3, 12
	s_cselect_b64 s[2:3], -1, 0
	v_writelane_b32 v250, s2, 41
	s_and_b64 s[0:1], s[2:3], s[0:1]
	s_andn2_b64 vcc, exec, s[0:1]
	v_writelane_b32 v250, s3, 42
	s_cbranch_vccnz .LBB0_1376
	v_readfirstlane_b32 s98, v198
	s_nop 3
	s_lshr_b32 s98, s98, 8
	s_cmp_eq_u32 s98, 0
	s_cbranch_scc1 .Lprio11_done
	s_setprio 1
.Lprio11_done:
	v_readlane_b32 s1, v251, 5
	s_and_b32 s0, s1, 0xffff
	v_bfe_u32 v1, v0, 10, 10
	v_bfe_u32 v0, v0, 20, 10
	v_mad_u32_u24 v199, v0, s0, v1
	v_mbcnt_lo_u32_b32 v0, -1, 0
	v_writelane_b32 v250, s94, 45
	s_lshl_b32 s91, s0, 8
	s_lshr_b32 s90, s1, 16
	s_add_i32 s33, s74, 0xfffff800
	s_mov_b32 s85, 0
	s_waitcnt vmcnt(0)
	v_mov_b32_e32 v155, 0
	s_movk_i32 s94, 0x1800
	s_movk_i32 s95, 0x90
	v_mov_b32_e32 v201, 0x1000
	v_mov_b32_e32 v203, 0x800
	v_mov_b32_e32 v210, 0x100
	v_mbcnt_hi_u32_b32 v211, -1, v0
	v_mov_b32_e32 v212, 0x1800
	s_branch .LBB0_1346

; __device__ __forceinline__ unsigned xb_ld(unsigned* p)              { return __hip_atomic_load(p, __ATOMIC_RELAXED, __HIP_MEMORY_SCOPE_AGENT); }
; __device__ __forceinline__ void xcd_barrier_complete(unsigned* bar, unsigned x, unsigned& nloc, unsigned& nx) {
;     const unsigned G = gridDim.x * gridDim.y * gridDim.z;
;     unsigned sum, cnt, mine, sp = 0u;
;     for (;;) {
;         sum = 0u; cnt = 0u; mine = 0u;
; #pragma unroll
;         for (unsigned j = 0; j < 16; ++j) { const unsigned c = xb_ld(&bar[XB_XCNT(j)]); sum += c; cnt += (c > 0u) ? 1u : 0u; mine = (j == x) ? c : mine; }
;         if (sum == G) break;
;         __builtin_amdgcn_s_sleep(1);
;         if ((++sp & 255u) == 0u) { if (xb_ld(&bar[XB_TMO])) break; if (sp > XB_SPIN_CAP) { atomicAdd(&bar[XB_TMO], 1u); break; } }
;     }
;     nloc = mine > 0u ? mine : 1u; nx = cnt > 0u ? cnt : 1u;
; }
; __device__ __forceinline__ void xcd_barrier(const XcdBarrier& b) {
;     asm volatile("s_waitcnt vmcnt(0)" ::: "memory");
;     __syncthreads();
;     if (threadIdx.x == 0) {
;         unsigned* bar = b.bar;
;         __builtin_amdgcn_s_waitcnt(0);
;         unsigned nloc = b.st[0], nx = b.st[1];
;         if (nloc == 0u) { xcd_barrier_complete(bar, b.x, nloc, nx); b.st[0] = nloc; b.st[1] = nx; }
.LBB0_1376:
	s_setprio 0
	s_cmp_gt_i32 s79, 12
	v_readlane_b32 s2, v250, 11
	s_cselect_b64 s[0:1], -1, 0
	v_readlane_b32 s3, v250, 12
	s_and_b64 s[2:3], s[2:3], s[0:1]
	s_and_b64 vcc, exec, s[2:3]
	s_cbranch_vccz .LBB0_1430
	s_waitcnt vmcnt(0)
	s_waitcnt vmcnt(0)
	s_barrier
	s_mov_b64 s[4:5], exec
	v_readlane_b32 s2, v251, 9
	v_readlane_b32 s3, v251, 10
	s_and_b64 s[2:3], s[4:5], s[2:3]
	s_mov_b64 exec, s[2:3]
	s_cbranch_execz .LBB0_1429
	s_add_u32 s6, s76, 0x4200
	s_mov_b32 s2, 0x20160
	s_addc_u32 s7, s77, 0
	s_addk_i32 s2, 0x100
	v_mov_b32_e32 v0, s2
	s_mov_b32 s2, 0x20164
	s_waitcnt vmcnt(0) expcnt(0) lgkmcnt(0)
	ds_read_b32 v2, v0
	s_addk_i32 s2, 0x100
	v_mov_b32_e32 v0, s2
	ds_read_b32 v0, v0
	s_waitcnt lgkmcnt(1)
	v_cmp_ne_u32_e32 vcc, 0, v2
	s_cbranch_vccnz .LBB0_1393
	v_readlane_b32 s8, v251, 1
	v_readlane_b32 s2, v251, 0
	v_readlane_b32 s9, v251, 2
	s_add_u32 s8, s76, 0x4400
	s_mul_i32 s2, s2, s9
	s_addc_u32 s9, s77, 0
	s_add_u32 s10, s76, 0x4500
	s_addc_u32 s11, s77, 0
	s_add_u32 s12, s76, 0x4600
	s_addc_u32 s13, s77, 0
	s_add_u32 s14, s76, 0x4700
	s_addc_u32 s15, s77, 0
	s_add_u32 s16, s76, 0x4800
	s_addc_u32 s17, s77, 0
	s_add_u32 s18, s76, 0x4900
	s_addc_u32 s19, s77, 0
	s_add_u32 s20, s76, 0x4a00
	s_addc_u32 s21, s77, 0
	s_add_u32 s22, s76, 0x4b00
	s_addc_u32 s23, s77, 0
	s_add_u32 s24, s76, 0x4c00
	s_addc_u32 s25, s77, 0
	s_add_u32 s26, s76, 0x4d00
	s_addc_u32 s27, s77, 0
	s_add_u32 s28, s76, 0x4e00
	s_addc_u32 s29, s77, 0
	s_add_u32 s30, s76, 0x4f00
	s_addc_u32 s31, s77, 0
	s_add_u32 s34, s76, 0x5000
	s_addc_u32 s35, s77, 0
	s_add_u32 s36, s76, 0x5100
	s_addc_u32 s37, s77, 0
	s_add_u32 s38, s76, 0x5200
	s_addc_u32 s39, s77, 0
	s_add_u32 s40, s76, 0x5300
	s_mul_i32 s2, s2, s96
	s_addc_u32 s41, s77, 0
	s_mov_b32 s3, 1
	v_mov_b32_e32 v16, 0
	s_branch .LBB0_1381
